# phase 4 prep: quarters 2,3 run three workgroup barriers (half a trip) behind quarters 0,1 so the two waves sharing a SIMD are in different sections of the trip
# speedup vs baseline: 1.0202x; 1.0132x over previous
.LBB0_268:
	v_mov_b32_e32 v141, 0
	v_lshlrev_b32_e32 v140, 4, v94
	v_lshl_add_u64 v[98:99], s[70:71], 0, v[140:141]
	s_mov_b64 s[6:7], 0x7600000
	v_lshl_add_u32 v133, v1, 15, 0
	v_lshlrev_b32_e32 v96, 2, v131
	v_lshl_add_u64 v[142:143], v[98:99], 0, s[6:7]
	s_mov_b64 s[6:7], 0x7630000
	v_add_u32_e32 v135, v133, v96
	v_lshlrev_b32_e32 v136, 4, v95
	v_lshl_add_u64 v[144:145], v[98:99], 0, s[6:7]
	s_mov_b64 s[6:7], 0x7660000
	v_sub_u32_e32 v97, v135, v136
	v_lshl_add_u64 v[146:147], v[98:99], 0, s[6:7]
	v_mul_u32_u24_e32 v98, 0x48, v134
	v_lshl_add_u32 v165, v98, 1, v97
	v_mov_b32_e32 v97, v141
	v_bfe_u32 v100, v0, 6, 1
	v_lshl_add_u64 v[96:97], s[70:71], 0, v[96:97]
	s_mov_b64 s[14:15], 0x15a08000
	v_add_u32_e32 v101, 0x1b00, v133
	v_cmp_gt_u32_e64 s[8:9], 64, v4
	v_lshl_add_u32 v161, v4, 2, v133
	v_cmp_gt_u32_e64 s[10:11], 8, v4
	v_lshl_add_u64 v[154:155], v[96:97], 0, s[14:15]
	v_and_b32_e32 v4, 64, v0
	v_cmp_eq_u32_e32 vcc, 0, v100
	v_mul_u32_u24_e32 v96, 0x48, v132
	v_lshl_or_b32 v149, v100, 5, v132
	v_lshl_add_u64 v[156:157], s[12:13], 0, v[140:141]
	v_cmp_ne_u32_e64 s[12:13], 0, v4
	v_cndmask_b32_e32 v4, v101, v133, vcc
	v_lshlrev_b32_e32 v99, 1, v96
	v_lshlrev_b32_e32 v96, 1, v132
	v_mov_b32_e32 v97, v141
	v_lshlrev_b32_e32 v148, 2, v94
	v_add3_u32 v167, v4, v99, v140
	v_add_u32_e32 v101, v133, v96
	v_lshl_add_u64 v[158:159], s[68:69], 0, v[96:97]
	v_cmp_gt_u32_e64 s[14:15], 32, v3
	v_add_u32_e32 v97, v133, v140
	v_lshrrev_b32_e32 v160, 2, v3
	v_lshlrev_b32_e32 v140, 1, v3
	v_lshlrev_b32_e32 v3, 2, v149
	v_add_u32_e32 v102, v101, v96
	v_lshl_or_b32 v96, v94, 10, v3
	v_or_b32_e32 v164, 1, v148
	v_add_u32_e32 v169, v133, v96
	v_lshl_or_b32 v96, v164, 8, v3
	v_or_b32_e32 v166, 2, v148
	v_add_u32_e32 v171, v133, v96
	v_lshl_or_b32 v96, v166, 8, v3
	v_cmp_lt_u32_e64 s[20:21], v132, v166
	v_add_u32_e32 v194, v133, v96
	v_or_b32_e32 v168, 3, v148
	v_cndmask_b32_e64 v96, 0, 1, s[20:21]
	v_cmp_le_u32_e64 s[20:21], v132, v166
	s_add_u32 s30, s70, 0x7900000
	v_lshl_or_b32 v3, v168, 8, v3
	v_add_u32_e32 v199, v97, v99
	v_cndmask_b32_e64 v99, 0, 1, s[20:21]
	s_addc_u32 s31, s71, 0
	v_add_u32_e32 v195, v133, v3
	v_mul_u32_u24_e32 v3, 0xc0, v95
	v_cndmask_b32_e32 v96, v99, v96, vcc
	s_add_u32 s42, s70, 0x9900000
	v_lshlrev_b32_e32 v150, 1, v134
	v_lshlrev_b32_e32 v3, 1, v3
	v_cmp_lt_u32_e64 s[16:17], v132, v148
	v_and_b32_e32 v96, 1, v96
	v_cmp_lt_u32_e64 s[22:23], v132, v168
	s_addc_u32 s43, s71, 0
	s_waitcnt lgkmcnt(0)
	s_load_dword s3, s[0:1], 0xd8
	v_add3_u32 v197, v133, v150, v3
	v_add3_u32 v198, v133, v3, v150
	v_cndmask_b32_e64 v3, 0, 1, s[16:17]
	v_cmp_le_u32_e64 s[16:17], v132, v148
	v_cmp_eq_u32_e64 s[20:21], 1, v96
	v_cndmask_b32_e64 v96, 0, 1, s[22:23]
	v_cmp_le_u32_e64 s[22:23], v132, v168
	s_add_u32 s46, s70, 0x15c08000
	v_cmp_eq_u32_e64 s[6:7], 0, v95
	v_lshlrev_b32_e32 v152, 1, v95
	v_cndmask_b32_e64 v95, 0, 1, s[16:17]
	v_cndmask_b32_e64 v99, 0, 1, s[22:23]
	s_addc_u32 s47, s71, 0
	s_movk_i32 s24, 0x210
	v_cndmask_b32_e32 v3, v95, v3, vcc
	v_cndmask_b32_e32 v96, v99, v96, vcc
	s_add_u32 s50, s70, 0xb900000
	v_and_b32_e32 v3, 1, v3
	v_and_b32_e32 v96, 1, v96
	s_movk_i32 s25, 0x840
	v_mad_u32_u24 v108, v164, s24, v133
	s_addc_u32 s51, s71, 0
	v_cmp_eq_u32_e64 s[16:17], 1, v3
	v_mul_u32_u24_e32 v3, 0x110, v94
	v_or_b32_e32 v95, v148, v100
	v_cmp_eq_u32_e64 s[22:23], 1, v96
	v_lshl_or_b32 v99, v100, 1, 1
	v_lshlrev_b32_e32 v96, 4, v100
	v_mul_u32_u24_e32 v104, 0xc0, v94
	v_lshlrev_b32_e32 v100, 7, v100
	v_mad_u32_u24 v94, v94, s25, v133
	v_lshlrev_b32_e32 v107, 2, v132
	v_add_u32_e32 v109, 0x210, v108
	v_add_u32_e32 v110, 0x420, v108
	s_waitcnt lgkmcnt(0)
	s_cmpk_lg_i32 s3, 0x100
	v_lshlrev_b32_e32 v4, 4, v0
	v_add3_u32 v200, v94, v100, v107
	v_add3_u32 v201, v108, v100, v107
	v_add3_u32 v202, v109, v100, v107
	v_add3_u32 v203, v110, v100, v107
	v_lshl_or_b32 v100, v99, 4, v132
	s_cselect_b64 s[52:53], -1, 0
	v_mul_u32_u24_e32 v98, 0x210, v134
	v_mul_u32_u24_e32 v103, 48, v132
	v_and_b32_e32 v4, 48, v4
	v_cmp_gt_u32_e64 s[18:19], v132, v95
	v_mul_u32_u24_e32 v95, 0x44, v164
	v_mul_u32_u24_e32 v105, 48, v164
	v_mul_u32_u24_e32 v106, 48, v149
	v_mul_u32_u24_e32 v100, 48, v100
	v_lshlrev_b32_e32 v99, 6, v99
	s_lshl_b32 s64, s3, 2
	v_lshl_add_u32 v153, v134, 8, v135
	v_mov_b32_e32 v137, v141
	v_mov_b32_e32 v151, v141
	v_lshl_add_u64 v[162:163], s[30:31], 0, v[140:141]
	v_or_b32_e32 v196, 16, v149
	v_or_b32_e32 v170, 1, v152
	v_add3_u32 v204, v94, v99, v107
	v_add3_u32 v205, v108, v99, v107
	v_add3_u32 v206, v109, v99, v107
	v_add3_u32 v207, v110, v99, v107
	s_lshl_b32 s65, s2, 2
	v_or_b32_e32 v208, s64, v1
	s_movk_i32 s66, 0xff0
	s_mov_b32 s67, 0xbfb8aa3b
	s_mov_b32 s74, 0x800000
	s_mov_b32 s75, 0x3f317217
	s_mov_b32 s76, 0x7f800000
	s_mov_b32 s77, 0xf800000
	v_mov_b32_e32 v209, 0x260
	v_add_u32_e32 v210, v135, v98
	s_movk_i32 s78, 0x3c0
	s_movk_i32 s79, 0x1800
	s_movk_i32 s80, 0x1000
	v_add_u32_e32 v211, v102, v3
	v_lshlrev_b32_e32 v172, 1, v96
	v_add_u32_e32 v212, v101, v104
	v_add_u32_e32 v213, v97, v106
	v_add_u32_e32 v214, v97, v100
	v_lshlrev_b32_e32 v174, 1, v4
	v_mov_b32_e32 v215, 0x41b17218
	v_add_u32_e32 v216, v102, v95
	v_add_u32_e32 v217, v101, v105
	v_add_u32_e32 v218, v97, v103
	s_mov_b32 s81, s2
	v_readfirstlane_b32 vcc_lo, v0
	s_nop 1
	s_lshr_b32 vcc_lo, vcc_lo, 6
	s_cmp_lt_u32 vcc_lo, 4
	s_cbranch_scc1 .Lprep_in
	s_barrier
	s_barrier
	s_barrier
.Lprep_in:
	s_branch .LBB0_270
.LBB0_269:
	s_or_b64 exec, exec, s[26:27]
	s_andn2_b64 vcc, exec, s[24:25]
	s_add_i32 s65, s65, s64
	s_cbranch_vccz .Lprep_out

.Lprep_out:
	v_readfirstlane_b32 vcc_lo, v0
	s_nop 1
	s_lshr_b32 vcc_lo, vcc_lo, 6
	s_cmp_gt_u32 vcc_lo, 3
	s_cbranch_scc1 .LBB0_326
	s_barrier
	s_barrier
	s_barrier
